# GEMM K-loops: same-accumulator MFMA pairs back to back AND accumulators ordered so the first source operand alternates between the two k-fragments of one row block for 8 MFMAs
# speedup vs baseline: 1.0147x; 1.0063x over previous
.LBB0_265:
	ds_read_b128 v[154:157], v161
	ds_read_b128 v[164:167], v161 offset:1024
	ds_read_b128 v[168:171], v161 offset:2048
	ds_read_b128 v[172:175], v161 offset:3072
	ds_read_b128 v[176:179], v162
	ds_read_b128 v[180:183], v162 offset:1024
	ds_read_b128 v[184:187], v162 offset:2048
	ds_read_b128 v[188:191], v162 offset:3072
	ds_read_b128 v[192:195], v163
	ds_read_b128 v[196:199], v163 offset:1024
	ds_read_b128 v[200:203], v163 offset:2048
	ds_read_b128 v[204:207], v163 offset:3072
	ds_read_b128 v[208:211], v163 offset:4096
	ds_read_b128 v[212:215], v163 offset:5120
	s_add_i32 m0, s33, 0xc000
	ds_read_b128 v[216:219], v163 offset:6144
	global_load_lds_dwordx4 v146, s[72:73]
	s_add_i32 m0, s33, 0xe000
	ds_read_b128 v[220:223], v163 offset:7168
	global_load_lds_dwordx4 v148, s[72:73]
	s_waitcnt vmcnt(8) lgkmcnt(0)
	s_barrier
	s_setprio 1
	v_mfma_f32_16x16x32_bf16 v[126:129], v[154:157], v[192:195], v[126:129]
	v_mfma_f32_16x16x32_bf16 v[126:129], v[164:167], v[196:199], v[126:129]
	v_mfma_f32_16x16x32_bf16 v[110:113], v[154:157], v[200:203], v[110:113]
	s_add_u32 s12, s72, 0xfff00080
	v_mfma_f32_16x16x32_bf16 v[110:113], v[164:167], v[204:207], v[110:113]
	s_addc_u32 s13, s73, -1
	v_mfma_f32_16x16x32_bf16 v[94:97], v[154:157], v[208:211], v[94:97]
	s_cmp_eq_u32 s83, 60
	v_mfma_f32_16x16x32_bf16 v[94:97], v[164:167], v[212:215], v[94:97]
	s_cselect_b32 s77, s55, s13
	v_mfma_f32_16x16x32_bf16 v[78:81], v[154:157], v[216:219], v[78:81]
	s_cselect_b32 s76, s71, s12
	v_mfma_f32_16x16x32_bf16 v[78:81], v[164:167], v[220:223], v[78:81]
	s_cselect_b32 s75, s53, s82
	v_mfma_f32_16x16x32_bf16 v[122:125], v[168:171], v[192:195], v[122:125]
	s_cselect_b32 s74, s80, s81
	v_mfma_f32_16x16x32_bf16 v[122:125], v[172:175], v[196:199], v[122:125]
	s_add_u32 s98, s74, 0x100000
	v_mfma_f32_16x16x32_bf16 v[106:109], v[168:171], v[200:203], v[106:109]
	s_addc_u32 s99, s75, 0
	v_mfma_f32_16x16x32_bf16 v[106:109], v[172:175], v[204:207], v[106:109]
	s_add_u32 s100, s76, 0x100000
	v_mfma_f32_16x16x32_bf16 v[90:93], v[168:171], v[208:211], v[90:93]
	s_addc_u32 s101, s77, 0
	v_mfma_f32_16x16x32_bf16 v[90:93], v[172:175], v[212:215], v[90:93]
	v_mfma_f32_16x16x32_bf16 v[74:77], v[168:171], v[216:219], v[74:77]
	v_mfma_f32_16x16x32_bf16 v[74:77], v[172:175], v[220:223], v[74:77]
	v_mfma_f32_16x16x32_bf16 v[118:121], v[176:179], v[192:195], v[118:121]
	v_mfma_f32_16x16x32_bf16 v[118:121], v[180:183], v[196:199], v[118:121]
	v_mfma_f32_16x16x32_bf16 v[102:105], v[176:179], v[200:203], v[102:105]
	v_mfma_f32_16x16x32_bf16 v[102:105], v[180:183], v[204:207], v[102:105]
	v_mfma_f32_16x16x32_bf16 v[86:89], v[176:179], v[208:211], v[86:89]
	v_mfma_f32_16x16x32_bf16 v[86:89], v[180:183], v[212:215], v[86:89]
	v_mfma_f32_16x16x32_bf16 v[70:73], v[176:179], v[216:219], v[70:73]
	v_mfma_f32_16x16x32_bf16 v[70:73], v[180:183], v[220:223], v[70:73]
	v_mfma_f32_16x16x32_bf16 v[114:117], v[184:187], v[192:195], v[114:117]
	v_mfma_f32_16x16x32_bf16 v[114:117], v[188:191], v[196:199], v[114:117]
	v_mfma_f32_16x16x32_bf16 v[98:101], v[184:187], v[200:203], v[98:101]
	v_mfma_f32_16x16x32_bf16 v[98:101], v[188:191], v[204:207], v[98:101]
	v_mfma_f32_16x16x32_bf16 v[82:85], v[184:187], v[208:211], v[82:85]
	v_mfma_f32_16x16x32_bf16 v[82:85], v[188:191], v[212:215], v[82:85]
	v_mfma_f32_16x16x32_bf16 v[66:69], v[184:187], v[216:219], v[66:69]
	v_mfma_f32_16x16x32_bf16 v[66:69], v[188:191], v[220:223], v[66:69]
	s_setprio 0
	s_barrier
	ds_read_b128 v[192:195], v163 offset:16384
	ds_read_b128 v[196:199], v163 offset:17408
	s_add_i32 m0, s33, 0x10000
	ds_read_b128 v[200:203], v163 offset:18432
	global_load_lds_dwordx4 v134, s[74:75]
	s_add_i32 m0, s33, 0x12000
	ds_read_b128 v[204:207], v163 offset:19456
	global_load_lds_dwordx4 v130, s[74:75]
	s_add_i32 m0, s33, 0x14000
	ds_read_b128 v[208:211], v163 offset:20480
	global_load_lds_dwordx4 v134, s[98:99]
	s_add_i32 m0, s33, 0x16000
	ds_read_b128 v[212:215], v163 offset:21504
	global_load_lds_dwordx4 v130, s[98:99]
	s_mov_b32 m0, s33
	ds_read_b128 v[216:219], v163 offset:22528
	global_load_lds_dwordx4 v136, s[76:77]
	s_add_i32 m0, s33, 0x2000
	ds_read_b128 v[220:223], v163 offset:23552
	global_load_lds_dwordx4 v132, s[76:77]
	s_waitcnt vmcnt(8) lgkmcnt(0)
	s_barrier
	s_setprio 1
	v_mfma_f32_16x16x32_bf16 v[62:65], v[154:157], v[192:195], v[62:65]
	v_mfma_f32_16x16x32_bf16 v[62:65], v[164:167], v[196:199], v[62:65]
	v_mfma_f32_16x16x32_bf16 v[46:49], v[154:157], v[200:203], v[46:49]
	v_mfma_f32_16x16x32_bf16 v[46:49], v[164:167], v[204:207], v[46:49]
	v_mfma_f32_16x16x32_bf16 v[30:33], v[154:157], v[208:211], v[30:33]
	v_mfma_f32_16x16x32_bf16 v[30:33], v[164:167], v[212:215], v[30:33]
	v_mfma_f32_16x16x32_bf16 v[14:17], v[154:157], v[216:219], v[14:17]
	v_mfma_f32_16x16x32_bf16 v[14:17], v[164:167], v[220:223], v[14:17]
	v_mfma_f32_16x16x32_bf16 v[58:61], v[168:171], v[192:195], v[58:61]
	v_mfma_f32_16x16x32_bf16 v[58:61], v[172:175], v[196:199], v[58:61]
	v_mfma_f32_16x16x32_bf16 v[42:45], v[168:171], v[200:203], v[42:45]
	v_mfma_f32_16x16x32_bf16 v[42:45], v[172:175], v[204:207], v[42:45]
	v_mfma_f32_16x16x32_bf16 v[26:29], v[168:171], v[208:211], v[26:29]
	v_mfma_f32_16x16x32_bf16 v[26:29], v[172:175], v[212:215], v[26:29]
	v_mfma_f32_16x16x32_bf16 v[10:13], v[168:171], v[216:219], v[10:13]
	v_mfma_f32_16x16x32_bf16 v[10:13], v[172:175], v[220:223], v[10:13]
	v_mfma_f32_16x16x32_bf16 v[54:57], v[176:179], v[192:195], v[54:57]
	v_mfma_f32_16x16x32_bf16 v[54:57], v[180:183], v[196:199], v[54:57]
	v_mfma_f32_16x16x32_bf16 v[38:41], v[176:179], v[200:203], v[38:41]
	v_mfma_f32_16x16x32_bf16 v[38:41], v[180:183], v[204:207], v[38:41]
	v_mfma_f32_16x16x32_bf16 v[22:25], v[176:179], v[208:211], v[22:25]
	v_mfma_f32_16x16x32_bf16 v[22:25], v[180:183], v[212:215], v[22:25]
	v_mfma_f32_16x16x32_bf16 v[6:9], v[176:179], v[216:219], v[6:9]
	v_mfma_f32_16x16x32_bf16 v[6:9], v[180:183], v[220:223], v[6:9]
	v_mfma_f32_16x16x32_bf16 v[50:53], v[184:187], v[192:195], v[50:53]
	v_mfma_f32_16x16x32_bf16 v[50:53], v[188:191], v[196:199], v[50:53]
	v_mfma_f32_16x16x32_bf16 v[34:37], v[184:187], v[200:203], v[34:37]
	v_mfma_f32_16x16x32_bf16 v[34:37], v[188:191], v[204:207], v[34:37]
	v_mfma_f32_16x16x32_bf16 v[18:21], v[184:187], v[208:211], v[18:21]
	v_mfma_f32_16x16x32_bf16 v[18:21], v[188:191], v[212:215], v[18:21]
	v_mfma_f32_16x16x32_bf16 v[2:5], v[184:187], v[216:219], v[2:5]
	v_mfma_f32_16x16x32_bf16 v[2:5], v[188:191], v[220:223], v[2:5]
	s_setprio 0
	s_barrier
	ds_read_b128 v[154:157], v226
	ds_read_b128 v[164:167], v226 offset:1024
	ds_read_b128 v[168:171], v226 offset:2048
	ds_read_b128 v[172:175], v226 offset:3072
	ds_read_b128 v[176:179], v227
	ds_read_b128 v[180:183], v227 offset:1024
	ds_read_b128 v[184:187], v227 offset:2048
	ds_read_b128 v[188:191], v227 offset:3072
	ds_read_b128 v[192:195], v163 offset:32768
	ds_read_b128 v[196:199], v163 offset:33792
	ds_read_b128 v[200:203], v163 offset:34816
	ds_read_b128 v[204:207], v163 offset:35840
	ds_read_b128 v[208:211], v163 offset:36864
	ds_read_b128 v[212:215], v163 offset:37888
	s_add_i32 m0, s33, 0x4000
	ds_read_b128 v[216:219], v163 offset:38912
	global_load_lds_dwordx4 v136, s[100:101]
	s_add_i32 m0, s33, 0x6000
	ds_read_b128 v[220:223], v163 offset:39936
	global_load_lds_dwordx4 v132, s[100:101]
	s_waitcnt vmcnt(8) lgkmcnt(0)
	s_barrier
	s_setprio 1
	v_mfma_f32_16x16x32_bf16 v[126:129], v[154:157], v[192:195], v[126:129]
	v_mfma_f32_16x16x32_bf16 v[126:129], v[164:167], v[196:199], v[126:129]
	v_mfma_f32_16x16x32_bf16 v[110:113], v[154:157], v[200:203], v[110:113]
	v_mfma_f32_16x16x32_bf16 v[110:113], v[164:167], v[204:207], v[110:113]
	v_mfma_f32_16x16x32_bf16 v[94:97], v[154:157], v[208:211], v[94:97]
	v_mfma_f32_16x16x32_bf16 v[94:97], v[164:167], v[212:215], v[94:97]
	v_mfma_f32_16x16x32_bf16 v[78:81], v[154:157], v[216:219], v[78:81]
	v_mfma_f32_16x16x32_bf16 v[78:81], v[164:167], v[220:223], v[78:81]
	v_mfma_f32_16x16x32_bf16 v[122:125], v[168:171], v[192:195], v[122:125]
	v_mfma_f32_16x16x32_bf16 v[122:125], v[172:175], v[196:199], v[122:125]
	v_mfma_f32_16x16x32_bf16 v[106:109], v[168:171], v[200:203], v[106:109]
	v_mfma_f32_16x16x32_bf16 v[106:109], v[172:175], v[204:207], v[106:109]
	v_mfma_f32_16x16x32_bf16 v[90:93], v[168:171], v[208:211], v[90:93]
	v_mfma_f32_16x16x32_bf16 v[90:93], v[172:175], v[212:215], v[90:93]
	v_mfma_f32_16x16x32_bf16 v[74:77], v[168:171], v[216:219], v[74:77]
	v_mfma_f32_16x16x32_bf16 v[74:77], v[172:175], v[220:223], v[74:77]
	v_mfma_f32_16x16x32_bf16 v[118:121], v[176:179], v[192:195], v[118:121]
	v_mfma_f32_16x16x32_bf16 v[118:121], v[180:183], v[196:199], v[118:121]
	v_mfma_f32_16x16x32_bf16 v[102:105], v[176:179], v[200:203], v[102:105]
	v_mfma_f32_16x16x32_bf16 v[102:105], v[180:183], v[204:207], v[102:105]
	v_mfma_f32_16x16x32_bf16 v[86:89], v[176:179], v[208:211], v[86:89]
	v_mfma_f32_16x16x32_bf16 v[86:89], v[180:183], v[212:215], v[86:89]
	v_mfma_f32_16x16x32_bf16 v[70:73], v[176:179], v[216:219], v[70:73]
	v_mfma_f32_16x16x32_bf16 v[70:73], v[180:183], v[220:223], v[70:73]
	v_mfma_f32_16x16x32_bf16 v[114:117], v[184:187], v[192:195], v[114:117]
	v_mfma_f32_16x16x32_bf16 v[114:117], v[188:191], v[196:199], v[114:117]
	v_mfma_f32_16x16x32_bf16 v[98:101], v[184:187], v[200:203], v[98:101]
	v_mfma_f32_16x16x32_bf16 v[98:101], v[188:191], v[204:207], v[98:101]
	v_mfma_f32_16x16x32_bf16 v[82:85], v[184:187], v[208:211], v[82:85]
	v_mfma_f32_16x16x32_bf16 v[82:85], v[188:191], v[212:215], v[82:85]
	v_mfma_f32_16x16x32_bf16 v[66:69], v[184:187], v[216:219], v[66:69]
	v_mfma_f32_16x16x32_bf16 v[66:69], v[188:191], v[220:223], v[66:69]
	s_setprio 0
	s_barrier
	ds_read_b128 v[192:195], v163 offset:49152
	ds_read_b128 v[196:199], v163 offset:50176
	s_add_i32 m0, s33, 0x17f80
	ds_read_b128 v[200:203], v163 offset:51200
	global_load_lds_dwordx4 v134, s[74:75] offset:128
	s_add_i32 m0, s33, 0x19f80
	ds_read_b128 v[204:207], v163 offset:52224
	global_load_lds_dwordx4 v130, s[74:75] offset:128
	s_add_i32 m0, s33, 0x1bf80
	ds_read_b128 v[208:211], v163 offset:53248
	global_load_lds_dwordx4 v134, s[98:99] offset:128
	s_add_i32 m0, s33, 0x1df80
	ds_read_b128 v[212:215], v163 offset:54272
	global_load_lds_dwordx4 v130, s[98:99] offset:128
	s_add_i32 m0, s33, 0x7f80
	ds_read_b128 v[216:219], v163 offset:55296
	global_load_lds_dwordx4 v136, s[76:77] offset:128
	s_add_i32 m0, s33, 0x9f80
	ds_read_b128 v[220:223], v163 offset:56320
	global_load_lds_dwordx4 v132, s[76:77] offset:128
	s_waitcnt vmcnt(8) lgkmcnt(0)
	s_barrier
	s_setprio 1
	v_mfma_f32_16x16x32_bf16 v[62:65], v[154:157], v[192:195], v[62:65]
	v_mfma_f32_16x16x32_bf16 v[62:65], v[164:167], v[196:199], v[62:65]
	v_mfma_f32_16x16x32_bf16 v[46:49], v[154:157], v[200:203], v[46:49]
	v_mfma_f32_16x16x32_bf16 v[46:49], v[164:167], v[204:207], v[46:49]
	v_mfma_f32_16x16x32_bf16 v[30:33], v[154:157], v[208:211], v[30:33]
	v_mfma_f32_16x16x32_bf16 v[30:33], v[164:167], v[212:215], v[30:33]
	v_mfma_f32_16x16x32_bf16 v[14:17], v[154:157], v[216:219], v[14:17]
	v_mfma_f32_16x16x32_bf16 v[14:17], v[164:167], v[220:223], v[14:17]
	v_mfma_f32_16x16x32_bf16 v[58:61], v[168:171], v[192:195], v[58:61]
	v_mfma_f32_16x16x32_bf16 v[58:61], v[172:175], v[196:199], v[58:61]
	v_mfma_f32_16x16x32_bf16 v[42:45], v[168:171], v[200:203], v[42:45]
	v_mfma_f32_16x16x32_bf16 v[42:45], v[172:175], v[204:207], v[42:45]
	v_mfma_f32_16x16x32_bf16 v[26:29], v[168:171], v[208:211], v[26:29]
	v_mfma_f32_16x16x32_bf16 v[26:29], v[172:175], v[212:215], v[26:29]
	v_mfma_f32_16x16x32_bf16 v[10:13], v[168:171], v[216:219], v[10:13]
	v_mfma_f32_16x16x32_bf16 v[10:13], v[172:175], v[220:223], v[10:13]
	v_mfma_f32_16x16x32_bf16 v[54:57], v[176:179], v[192:195], v[54:57]
	v_mfma_f32_16x16x32_bf16 v[54:57], v[180:183], v[196:199], v[54:57]
	v_mfma_f32_16x16x32_bf16 v[38:41], v[176:179], v[200:203], v[38:41]
	v_mfma_f32_16x16x32_bf16 v[38:41], v[180:183], v[204:207], v[38:41]
	v_mfma_f32_16x16x32_bf16 v[22:25], v[176:179], v[208:211], v[22:25]
	v_mfma_f32_16x16x32_bf16 v[22:25], v[180:183], v[212:215], v[22:25]
	v_mfma_f32_16x16x32_bf16 v[6:9], v[176:179], v[216:219], v[6:9]
	v_mfma_f32_16x16x32_bf16 v[6:9], v[180:183], v[220:223], v[6:9]
	v_mfma_f32_16x16x32_bf16 v[50:53], v[184:187], v[192:195], v[50:53]
	v_mfma_f32_16x16x32_bf16 v[50:53], v[188:191], v[196:199], v[50:53]
	s_add_i32 s83, s83, 2
	v_mfma_f32_16x16x32_bf16 v[34:37], v[184:187], v[200:203], v[34:37]
	s_add_u32 s72, s72, 0x100
	v_mfma_f32_16x16x32_bf16 v[34:37], v[188:191], v[204:207], v[34:37]
	s_addc_u32 s73, s73, 0
	v_mfma_f32_16x16x32_bf16 v[18:21], v[184:187], v[208:211], v[18:21]
	s_add_u32 s81, s81, 0x100
	v_mfma_f32_16x16x32_bf16 v[18:21], v[188:191], v[212:215], v[18:21]
	s_addc_u32 s82, s82, 0
	v_mfma_f32_16x16x32_bf16 v[2:5], v[184:187], v[216:219], v[2:5]
	s_cmp_gt_u32 s83, 61
	v_mfma_f32_16x16x32_bf16 v[2:5], v[188:191], v[220:223], v[2:5]
	s_setprio 0
	s_barrier
	s_cbranch_scc0 .LBB0_265
	s_and_b64 vcc, exec, s[46:47]
	s_cbranch_vccz .LBB0_268
	s_barrier

.LBB0_510:
	ds_read_b128 v[146:149], v152
	ds_read_b128 v[156:159], v152 offset:1024
	ds_read_b128 v[160:163], v152 offset:2048
	ds_read_b128 v[164:167], v152 offset:3072
	ds_read_b128 v[168:171], v153
	ds_read_b128 v[172:175], v153 offset:1024
	ds_read_b128 v[176:179], v153 offset:2048
	ds_read_b128 v[180:183], v153 offset:3072
	ds_read_b128 v[184:187], v154
	ds_read_b128 v[188:191], v154 offset:1024
	ds_read_b128 v[192:195], v154 offset:2048
	ds_read_b128 v[196:199], v154 offset:3072
	ds_read_b128 v[206:209], v154 offset:4096
	ds_read_b128 v[210:213], v154 offset:5120
	s_add_i32 m0, s1, 0xc000
	ds_read_b128 v[214:217], v154 offset:6144
	global_load_lds_dwordx4 v138, s[52:53]
	s_add_i32 m0, s1, 0xe000
	ds_read_b128 v[218:221], v154 offset:7168
	global_load_lds_dwordx4 v140, s[52:53]
	s_waitcnt vmcnt(8) lgkmcnt(0)
	s_barrier
	s_setprio 1
	v_mfma_f32_16x16x32_bf16 v[126:129], v[146:149], v[184:187], v[126:129]
	v_mfma_f32_16x16x32_bf16 v[126:129], v[156:159], v[188:191], v[126:129]
	v_mfma_f32_16x16x32_bf16 v[110:113], v[146:149], v[192:195], v[110:113]
	s_add_u32 s34, s52, 0xfff00080
	v_mfma_f32_16x16x32_bf16 v[110:113], v[156:159], v[196:199], v[110:113]
	s_addc_u32 s36, s53, -1
	v_mfma_f32_16x16x32_bf16 v[94:97], v[146:149], v[206:209], v[94:97]
	s_cmp_eq_u32 s62, 60
	v_mfma_f32_16x16x32_bf16 v[94:97], v[156:159], v[210:213], v[94:97]
	s_cselect_b32 s67, s45, s36
	v_mfma_f32_16x16x32_bf16 v[78:81], v[146:149], v[214:217], v[78:81]
	s_cselect_b32 s66, s51, s34
	v_mfma_f32_16x16x32_bf16 v[78:81], v[156:159], v[218:221], v[78:81]
	s_cselect_b32 s55, s23, s61
	v_mfma_f32_16x16x32_bf16 v[122:125], v[160:163], v[184:187], v[122:125]
	s_cselect_b32 s54, s59, s60
	v_mfma_f32_16x16x32_bf16 v[122:125], v[164:167], v[188:191], v[122:125]
	s_add_u32 s98, s54, 0x100000
	v_mfma_f32_16x16x32_bf16 v[106:109], v[160:163], v[192:195], v[106:109]
	s_addc_u32 s99, s55, 0
	v_mfma_f32_16x16x32_bf16 v[106:109], v[164:167], v[196:199], v[106:109]
	s_add_u32 s100, s66, 0x100000
	v_mfma_f32_16x16x32_bf16 v[90:93], v[160:163], v[206:209], v[90:93]
	s_addc_u32 s101, s67, 0
	v_mfma_f32_16x16x32_bf16 v[90:93], v[164:167], v[210:213], v[90:93]
	v_mfma_f32_16x16x32_bf16 v[74:77], v[160:163], v[214:217], v[74:77]
	v_mfma_f32_16x16x32_bf16 v[74:77], v[164:167], v[218:221], v[74:77]
	v_mfma_f32_16x16x32_bf16 v[118:121], v[168:171], v[184:187], v[118:121]
	v_mfma_f32_16x16x32_bf16 v[118:121], v[172:175], v[188:191], v[118:121]
	v_mfma_f32_16x16x32_bf16 v[102:105], v[168:171], v[192:195], v[102:105]
	v_mfma_f32_16x16x32_bf16 v[102:105], v[172:175], v[196:199], v[102:105]
	v_mfma_f32_16x16x32_bf16 v[86:89], v[168:171], v[206:209], v[86:89]
	v_mfma_f32_16x16x32_bf16 v[86:89], v[172:175], v[210:213], v[86:89]
	v_mfma_f32_16x16x32_bf16 v[70:73], v[168:171], v[214:217], v[70:73]
	v_mfma_f32_16x16x32_bf16 v[70:73], v[172:175], v[218:221], v[70:73]
	v_mfma_f32_16x16x32_bf16 v[114:117], v[176:179], v[184:187], v[114:117]
	v_mfma_f32_16x16x32_bf16 v[114:117], v[180:183], v[188:191], v[114:117]
	v_mfma_f32_16x16x32_bf16 v[98:101], v[176:179], v[192:195], v[98:101]
	v_mfma_f32_16x16x32_bf16 v[98:101], v[180:183], v[196:199], v[98:101]
	v_mfma_f32_16x16x32_bf16 v[82:85], v[176:179], v[206:209], v[82:85]
	v_mfma_f32_16x16x32_bf16 v[82:85], v[180:183], v[210:213], v[82:85]
	v_mfma_f32_16x16x32_bf16 v[66:69], v[176:179], v[214:217], v[66:69]
	v_mfma_f32_16x16x32_bf16 v[66:69], v[180:183], v[218:221], v[66:69]
	s_setprio 0
	s_barrier
	ds_read_b128 v[184:187], v154 offset:16384
	ds_read_b128 v[188:191], v154 offset:17408
	s_add_i32 m0, s1, 0x10000
	ds_read_b128 v[192:195], v154 offset:18432
	global_load_lds_dwordx4 v132, s[54:55]
	s_add_i32 m0, s1, 0x12000
	ds_read_b128 v[196:199], v154 offset:19456
	global_load_lds_dwordx4 v136, s[54:55]
	s_add_i32 m0, s1, 0x14000
	ds_read_b128 v[206:209], v154 offset:20480
	global_load_lds_dwordx4 v132, s[98:99]
	s_add_i32 m0, s1, 0x16000
	ds_read_b128 v[210:213], v154 offset:21504
	global_load_lds_dwordx4 v136, s[98:99]
	s_mov_b32 m0, s1
	ds_read_b128 v[214:217], v154 offset:22528
	global_load_lds_dwordx4 v130, s[66:67]
	s_add_i32 m0, s1, 0x2000
	ds_read_b128 v[218:221], v154 offset:23552
	global_load_lds_dwordx4 v134, s[66:67]
	s_waitcnt vmcnt(8) lgkmcnt(0)
	s_barrier
	s_setprio 1
	v_mfma_f32_16x16x32_bf16 v[62:65], v[146:149], v[184:187], v[62:65]
	v_mfma_f32_16x16x32_bf16 v[62:65], v[156:159], v[188:191], v[62:65]
	v_mfma_f32_16x16x32_bf16 v[46:49], v[146:149], v[192:195], v[46:49]
	v_mfma_f32_16x16x32_bf16 v[46:49], v[156:159], v[196:199], v[46:49]
	v_mfma_f32_16x16x32_bf16 v[30:33], v[146:149], v[206:209], v[30:33]
	v_mfma_f32_16x16x32_bf16 v[30:33], v[156:159], v[210:213], v[30:33]
	v_mfma_f32_16x16x32_bf16 v[14:17], v[146:149], v[214:217], v[14:17]
	v_mfma_f32_16x16x32_bf16 v[14:17], v[156:159], v[218:221], v[14:17]
	v_mfma_f32_16x16x32_bf16 v[58:61], v[160:163], v[184:187], v[58:61]
	v_mfma_f32_16x16x32_bf16 v[58:61], v[164:167], v[188:191], v[58:61]
	v_mfma_f32_16x16x32_bf16 v[42:45], v[160:163], v[192:195], v[42:45]
	v_mfma_f32_16x16x32_bf16 v[42:45], v[164:167], v[196:199], v[42:45]
	v_mfma_f32_16x16x32_bf16 v[26:29], v[160:163], v[206:209], v[26:29]
	v_mfma_f32_16x16x32_bf16 v[26:29], v[164:167], v[210:213], v[26:29]
	v_mfma_f32_16x16x32_bf16 v[10:13], v[160:163], v[214:217], v[10:13]
	v_mfma_f32_16x16x32_bf16 v[10:13], v[164:167], v[218:221], v[10:13]
	v_mfma_f32_16x16x32_bf16 v[54:57], v[168:171], v[184:187], v[54:57]
	v_mfma_f32_16x16x32_bf16 v[54:57], v[172:175], v[188:191], v[54:57]
	v_mfma_f32_16x16x32_bf16 v[38:41], v[168:171], v[192:195], v[38:41]
	v_mfma_f32_16x16x32_bf16 v[38:41], v[172:175], v[196:199], v[38:41]
	v_mfma_f32_16x16x32_bf16 v[22:25], v[168:171], v[206:209], v[22:25]
	v_mfma_f32_16x16x32_bf16 v[22:25], v[172:175], v[210:213], v[22:25]
	v_mfma_f32_16x16x32_bf16 v[6:9], v[168:171], v[214:217], v[6:9]
	v_mfma_f32_16x16x32_bf16 v[6:9], v[172:175], v[218:221], v[6:9]
	v_mfma_f32_16x16x32_bf16 v[50:53], v[176:179], v[184:187], v[50:53]
	v_mfma_f32_16x16x32_bf16 v[50:53], v[180:183], v[188:191], v[50:53]
	v_mfma_f32_16x16x32_bf16 v[34:37], v[176:179], v[192:195], v[34:37]
	v_mfma_f32_16x16x32_bf16 v[34:37], v[180:183], v[196:199], v[34:37]
	v_mfma_f32_16x16x32_bf16 v[18:21], v[176:179], v[206:209], v[18:21]
	v_mfma_f32_16x16x32_bf16 v[18:21], v[180:183], v[210:213], v[18:21]
	v_mfma_f32_16x16x32_bf16 v[2:5], v[176:179], v[214:217], v[2:5]
	v_mfma_f32_16x16x32_bf16 v[2:5], v[180:183], v[218:221], v[2:5]
	s_setprio 0
	s_barrier
	ds_read_b128 v[146:149], v226
	ds_read_b128 v[156:159], v226 offset:1024
	ds_read_b128 v[160:163], v226 offset:2048
	ds_read_b128 v[164:167], v226 offset:3072
	ds_read_b128 v[168:171], v227
	ds_read_b128 v[172:175], v227 offset:1024
	ds_read_b128 v[176:179], v227 offset:2048
	ds_read_b128 v[180:183], v227 offset:3072
	ds_read_b128 v[184:187], v154 offset:32768
	ds_read_b128 v[188:191], v154 offset:33792
	ds_read_b128 v[192:195], v154 offset:34816
	ds_read_b128 v[196:199], v154 offset:35840
	ds_read_b128 v[206:209], v154 offset:36864
	ds_read_b128 v[210:213], v154 offset:37888
	s_add_i32 m0, s1, 0x4000
	ds_read_b128 v[214:217], v154 offset:38912
	global_load_lds_dwordx4 v130, s[100:101]
	s_add_i32 m0, s1, 0x6000
	ds_read_b128 v[218:221], v154 offset:39936
	global_load_lds_dwordx4 v134, s[100:101]
	s_waitcnt vmcnt(8) lgkmcnt(0)
	s_barrier
	s_setprio 1
	v_mfma_f32_16x16x32_bf16 v[126:129], v[146:149], v[184:187], v[126:129]
	v_mfma_f32_16x16x32_bf16 v[126:129], v[156:159], v[188:191], v[126:129]
	v_mfma_f32_16x16x32_bf16 v[110:113], v[146:149], v[192:195], v[110:113]
	v_mfma_f32_16x16x32_bf16 v[110:113], v[156:159], v[196:199], v[110:113]
	v_mfma_f32_16x16x32_bf16 v[94:97], v[146:149], v[206:209], v[94:97]
	v_mfma_f32_16x16x32_bf16 v[94:97], v[156:159], v[210:213], v[94:97]
	v_mfma_f32_16x16x32_bf16 v[78:81], v[146:149], v[214:217], v[78:81]
	v_mfma_f32_16x16x32_bf16 v[78:81], v[156:159], v[218:221], v[78:81]
	v_mfma_f32_16x16x32_bf16 v[122:125], v[160:163], v[184:187], v[122:125]
	v_mfma_f32_16x16x32_bf16 v[122:125], v[164:167], v[188:191], v[122:125]
	v_mfma_f32_16x16x32_bf16 v[106:109], v[160:163], v[192:195], v[106:109]
	v_mfma_f32_16x16x32_bf16 v[106:109], v[164:167], v[196:199], v[106:109]
	v_mfma_f32_16x16x32_bf16 v[90:93], v[160:163], v[206:209], v[90:93]
	v_mfma_f32_16x16x32_bf16 v[90:93], v[164:167], v[210:213], v[90:93]
	v_mfma_f32_16x16x32_bf16 v[74:77], v[160:163], v[214:217], v[74:77]
	v_mfma_f32_16x16x32_bf16 v[74:77], v[164:167], v[218:221], v[74:77]
	v_mfma_f32_16x16x32_bf16 v[118:121], v[168:171], v[184:187], v[118:121]
	v_mfma_f32_16x16x32_bf16 v[118:121], v[172:175], v[188:191], v[118:121]
	v_mfma_f32_16x16x32_bf16 v[102:105], v[168:171], v[192:195], v[102:105]
	v_mfma_f32_16x16x32_bf16 v[102:105], v[172:175], v[196:199], v[102:105]
	v_mfma_f32_16x16x32_bf16 v[86:89], v[168:171], v[206:209], v[86:89]
	v_mfma_f32_16x16x32_bf16 v[86:89], v[172:175], v[210:213], v[86:89]
	v_mfma_f32_16x16x32_bf16 v[70:73], v[168:171], v[214:217], v[70:73]
	v_mfma_f32_16x16x32_bf16 v[70:73], v[172:175], v[218:221], v[70:73]
	v_mfma_f32_16x16x32_bf16 v[114:117], v[176:179], v[184:187], v[114:117]
	v_mfma_f32_16x16x32_bf16 v[114:117], v[180:183], v[188:191], v[114:117]
	v_mfma_f32_16x16x32_bf16 v[98:101], v[176:179], v[192:195], v[98:101]
	v_mfma_f32_16x16x32_bf16 v[98:101], v[180:183], v[196:199], v[98:101]
	v_mfma_f32_16x16x32_bf16 v[82:85], v[176:179], v[206:209], v[82:85]
	v_mfma_f32_16x16x32_bf16 v[82:85], v[180:183], v[210:213], v[82:85]
	v_mfma_f32_16x16x32_bf16 v[66:69], v[176:179], v[214:217], v[66:69]
	v_mfma_f32_16x16x32_bf16 v[66:69], v[180:183], v[218:221], v[66:69]
	s_setprio 0
	s_barrier
	ds_read_b128 v[184:187], v154 offset:49152
	ds_read_b128 v[188:191], v154 offset:50176
	s_add_i32 m0, s1, 0x17f80
	ds_read_b128 v[192:195], v154 offset:51200
	global_load_lds_dwordx4 v132, s[54:55] offset:128
	s_add_i32 m0, s1, 0x19f80
	ds_read_b128 v[196:199], v154 offset:52224
	global_load_lds_dwordx4 v136, s[54:55] offset:128
	s_add_i32 m0, s1, 0x1bf80
	ds_read_b128 v[206:209], v154 offset:53248
	global_load_lds_dwordx4 v132, s[98:99] offset:128
	s_add_i32 m0, s1, 0x1df80
	ds_read_b128 v[210:213], v154 offset:54272
	global_load_lds_dwordx4 v136, s[98:99] offset:128
	s_add_i32 m0, s1, 0x7f80
	ds_read_b128 v[214:217], v154 offset:55296
	global_load_lds_dwordx4 v130, s[66:67] offset:128
	s_add_i32 m0, s1, 0x9f80
	ds_read_b128 v[218:221], v154 offset:56320
	global_load_lds_dwordx4 v134, s[66:67] offset:128
	s_waitcnt vmcnt(8) lgkmcnt(0)
	s_barrier
	s_setprio 1
	v_mfma_f32_16x16x32_bf16 v[62:65], v[146:149], v[184:187], v[62:65]
	v_mfma_f32_16x16x32_bf16 v[62:65], v[156:159], v[188:191], v[62:65]
	v_mfma_f32_16x16x32_bf16 v[46:49], v[146:149], v[192:195], v[46:49]
	v_mfma_f32_16x16x32_bf16 v[46:49], v[156:159], v[196:199], v[46:49]
	v_mfma_f32_16x16x32_bf16 v[30:33], v[146:149], v[206:209], v[30:33]
	v_mfma_f32_16x16x32_bf16 v[30:33], v[156:159], v[210:213], v[30:33]
	v_mfma_f32_16x16x32_bf16 v[14:17], v[146:149], v[214:217], v[14:17]
	v_mfma_f32_16x16x32_bf16 v[14:17], v[156:159], v[218:221], v[14:17]
	v_mfma_f32_16x16x32_bf16 v[58:61], v[160:163], v[184:187], v[58:61]
	v_mfma_f32_16x16x32_bf16 v[58:61], v[164:167], v[188:191], v[58:61]
	v_mfma_f32_16x16x32_bf16 v[42:45], v[160:163], v[192:195], v[42:45]
	v_mfma_f32_16x16x32_bf16 v[42:45], v[164:167], v[196:199], v[42:45]
	v_mfma_f32_16x16x32_bf16 v[26:29], v[160:163], v[206:209], v[26:29]
	v_mfma_f32_16x16x32_bf16 v[26:29], v[164:167], v[210:213], v[26:29]
	v_mfma_f32_16x16x32_bf16 v[10:13], v[160:163], v[214:217], v[10:13]
	v_mfma_f32_16x16x32_bf16 v[10:13], v[164:167], v[218:221], v[10:13]
	v_mfma_f32_16x16x32_bf16 v[54:57], v[168:171], v[184:187], v[54:57]
	v_mfma_f32_16x16x32_bf16 v[54:57], v[172:175], v[188:191], v[54:57]
	v_mfma_f32_16x16x32_bf16 v[38:41], v[168:171], v[192:195], v[38:41]
	v_mfma_f32_16x16x32_bf16 v[38:41], v[172:175], v[196:199], v[38:41]
	v_mfma_f32_16x16x32_bf16 v[22:25], v[168:171], v[206:209], v[22:25]
	v_mfma_f32_16x16x32_bf16 v[22:25], v[172:175], v[210:213], v[22:25]
	v_mfma_f32_16x16x32_bf16 v[6:9], v[168:171], v[214:217], v[6:9]
	v_mfma_f32_16x16x32_bf16 v[6:9], v[172:175], v[218:221], v[6:9]
	v_mfma_f32_16x16x32_bf16 v[50:53], v[176:179], v[184:187], v[50:53]
	v_mfma_f32_16x16x32_bf16 v[50:53], v[180:183], v[188:191], v[50:53]
	s_add_i32 s62, s62, 2
	v_mfma_f32_16x16x32_bf16 v[34:37], v[176:179], v[192:195], v[34:37]
	s_add_u32 s60, s60, 0x100
	v_mfma_f32_16x16x32_bf16 v[34:37], v[180:183], v[196:199], v[34:37]
	s_addc_u32 s61, s61, 0
	v_mfma_f32_16x16x32_bf16 v[18:21], v[176:179], v[206:209], v[18:21]
	s_add_u32 s52, s52, 0x100
	v_mfma_f32_16x16x32_bf16 v[18:21], v[180:183], v[210:213], v[18:21]
	s_addc_u32 s53, s53, 0
	v_mfma_f32_16x16x32_bf16 v[2:5], v[176:179], v[214:217], v[2:5]
	s_cmp_gt_u32 s62, 61
	v_mfma_f32_16x16x32_bf16 v[2:5], v[180:183], v[218:221], v[2:5]
	s_setprio 0
	s_barrier
	s_cbranch_scc0 .LBB0_510
	s_and_b64 vcc, exec, s[20:21]
	s_cbranch_vccz .LBB0_513
	s_barrier

.LBB0_651:
	ds_read_b128 v[130:133], v210
	ds_read_b128 v[134:137], v210 offset:1024
	ds_read_b128 v[138:141], v210 offset:2048
	ds_read_b128 v[142:145], v210 offset:3072
	ds_read_b128 v[146:149], v211
	ds_read_b128 v[150:153], v211 offset:1024
	ds_read_b128 v[154:157], v211 offset:2048
	ds_read_b128 v[158:161], v211 offset:3072
	ds_read_b128 v[162:165], v212
	ds_read_b128 v[166:169], v212 offset:1024
	ds_read_b128 v[188:191], v212 offset:2048
	ds_read_b128 v[192:195], v212 offset:3072
	ds_read_b128 v[196:199], v212 offset:4096
	ds_read_b128 v[214:217], v212 offset:5120
	s_add_i32 m0, s39, 0xc000
	ds_read_b128 v[218:221], v212 offset:6144
	global_load_lds_dwordx4 v180, s[88:89]
	s_add_i32 m0, s39, 0xe000
	ds_read_b128 v[222:225], v212 offset:7168
	global_load_lds_dwordx4 v182, s[88:89]
	s_waitcnt vmcnt(8) lgkmcnt(0)
	s_barrier
	s_setprio 1
	v_mfma_f32_16x16x32_bf16 v[126:129], v[130:133], v[162:165], v[126:129]
	v_mfma_f32_16x16x32_bf16 v[126:129], v[134:137], v[166:169], v[126:129]
	v_mfma_f32_16x16x32_bf16 v[122:125], v[130:133], v[188:191], v[122:125]
	s_add_u32 s90, s88, 0x100
	v_mfma_f32_16x16x32_bf16 v[122:125], v[134:137], v[192:195], v[122:125]
	s_addc_u32 s91, s89, 0
	v_mfma_f32_16x16x32_bf16 v[110:113], v[130:133], v[196:199], v[110:113]
	s_cmp_eq_u32 s66, 60
	v_mfma_f32_16x16x32_bf16 v[110:113], v[134:137], v[214:217], v[110:113]
	s_cselect_b32 s95, s79, s91
	v_mfma_f32_16x16x32_bf16 v[106:109], v[130:133], v[218:221], v[106:109]
	s_cselect_b32 s94, s85, s90
	v_mfma_f32_16x16x32_bf16 v[106:109], v[134:137], v[222:225], v[106:109]
	s_cselect_b32 s93, s77, vcc_hi
	v_mfma_f32_16x16x32_bf16 v[62:65], v[138:141], v[162:165], v[62:65]
	s_cselect_b32 s92, s87, vcc_lo
	v_mfma_f32_16x16x32_bf16 v[62:65], v[142:145], v[166:169], v[62:65]
	s_add_u32 s98, s92, 0x100000
	v_mfma_f32_16x16x32_bf16 v[58:61], v[138:141], v[188:191], v[58:61]
	s_addc_u32 s99, s93, 0
	v_mfma_f32_16x16x32_bf16 v[58:61], v[142:145], v[192:195], v[58:61]
	s_add_u32 s100, s94, 0x100000
	v_mfma_f32_16x16x32_bf16 v[50:53], v[138:141], v[196:199], v[50:53]
	s_addc_u32 s101, s95, 0
	v_mfma_f32_16x16x32_bf16 v[50:53], v[142:145], v[214:217], v[50:53]
	v_mfma_f32_16x16x32_bf16 v[42:45], v[138:141], v[218:221], v[42:45]
	v_mfma_f32_16x16x32_bf16 v[42:45], v[142:145], v[222:225], v[42:45]
	v_mfma_f32_16x16x32_bf16 v[118:121], v[146:149], v[162:165], v[118:121]
	v_mfma_f32_16x16x32_bf16 v[118:121], v[150:153], v[166:169], v[118:121]
	v_mfma_f32_16x16x32_bf16 v[114:117], v[146:149], v[188:191], v[114:117]
	v_mfma_f32_16x16x32_bf16 v[114:117], v[150:153], v[192:195], v[114:117]
	v_mfma_f32_16x16x32_bf16 v[102:105], v[146:149], v[196:199], v[102:105]
	v_mfma_f32_16x16x32_bf16 v[102:105], v[150:153], v[214:217], v[102:105]
	v_mfma_f32_16x16x32_bf16 v[98:101], v[146:149], v[218:221], v[98:101]
	v_mfma_f32_16x16x32_bf16 v[98:101], v[150:153], v[222:225], v[98:101]
	v_mfma_f32_16x16x32_bf16 v[54:57], v[154:157], v[162:165], v[54:57]
	v_mfma_f32_16x16x32_bf16 v[54:57], v[158:161], v[166:169], v[54:57]
	v_mfma_f32_16x16x32_bf16 v[46:49], v[154:157], v[188:191], v[46:49]
	v_mfma_f32_16x16x32_bf16 v[46:49], v[158:161], v[192:195], v[46:49]
	v_mfma_f32_16x16x32_bf16 v[38:41], v[154:157], v[196:199], v[38:41]
	v_mfma_f32_16x16x32_bf16 v[38:41], v[158:161], v[214:217], v[38:41]
	v_mfma_f32_16x16x32_bf16 v[34:37], v[154:157], v[218:221], v[34:37]
	v_mfma_f32_16x16x32_bf16 v[34:37], v[158:161], v[222:225], v[34:37]
	s_setprio 0
	s_barrier
	ds_read_b128 v[162:165], v212 offset:16384
	ds_read_b128 v[166:169], v212 offset:17408
	s_add_i32 m0, s39, 0x10000
	ds_read_b128 v[188:191], v212 offset:18432
	global_load_lds_dwordx4 v172, s[92:93]
	s_add_i32 m0, s39, 0x12000
	ds_read_b128 v[192:195], v212 offset:19456
	global_load_lds_dwordx4 v176, s[92:93]
	s_add_i32 m0, s39, 0x14000
	ds_read_b128 v[196:199], v212 offset:20480
	global_load_lds_dwordx4 v172, s[98:99]
	s_add_i32 m0, s39, 0x16000
	ds_read_b128 v[214:217], v212 offset:21504
	global_load_lds_dwordx4 v176, s[98:99]
	s_mov_b32 m0, s39
	ds_read_b128 v[218:221], v212 offset:22528
	global_load_lds_dwordx4 v170, s[94:95]
	s_add_i32 m0, s39, 0x2000
	ds_read_b128 v[222:225], v212 offset:23552
	global_load_lds_dwordx4 v174, s[94:95]
	s_waitcnt vmcnt(8) lgkmcnt(0)
	s_barrier
	s_setprio 1
	v_mfma_f32_16x16x32_bf16 v[94:97], v[130:133], v[162:165], v[94:97]
	v_mfma_f32_16x16x32_bf16 v[94:97], v[134:137], v[166:169], v[94:97]
	v_mfma_f32_16x16x32_bf16 v[90:93], v[130:133], v[188:191], v[90:93]
	v_mfma_f32_16x16x32_bf16 v[90:93], v[134:137], v[192:195], v[90:93]
	v_mfma_f32_16x16x32_bf16 v[82:85], v[130:133], v[196:199], v[82:85]
	v_mfma_f32_16x16x32_bf16 v[82:85], v[134:137], v[214:217], v[82:85]
	v_mfma_f32_16x16x32_bf16 v[74:77], v[130:133], v[218:221], v[74:77]
	v_mfma_f32_16x16x32_bf16 v[74:77], v[134:137], v[222:225], v[74:77]
	v_mfma_f32_16x16x32_bf16 v[30:33], v[138:141], v[162:165], v[30:33]
	v_mfma_f32_16x16x32_bf16 v[30:33], v[142:145], v[166:169], v[30:33]
	v_mfma_f32_16x16x32_bf16 v[26:29], v[138:141], v[188:191], v[26:29]
	v_mfma_f32_16x16x32_bf16 v[26:29], v[142:145], v[192:195], v[26:29]
	v_mfma_f32_16x16x32_bf16 v[18:21], v[138:141], v[196:199], v[18:21]
	v_mfma_f32_16x16x32_bf16 v[18:21], v[142:145], v[214:217], v[18:21]
	v_mfma_f32_16x16x32_bf16 v[10:13], v[138:141], v[218:221], v[10:13]
	v_mfma_f32_16x16x32_bf16 v[10:13], v[142:145], v[222:225], v[10:13]
	v_mfma_f32_16x16x32_bf16 v[86:89], v[146:149], v[162:165], v[86:89]
	v_mfma_f32_16x16x32_bf16 v[86:89], v[150:153], v[166:169], v[86:89]
	v_mfma_f32_16x16x32_bf16 v[78:81], v[146:149], v[188:191], v[78:81]
	v_mfma_f32_16x16x32_bf16 v[78:81], v[150:153], v[192:195], v[78:81]
	v_mfma_f32_16x16x32_bf16 v[70:73], v[146:149], v[196:199], v[70:73]
	v_mfma_f32_16x16x32_bf16 v[70:73], v[150:153], v[214:217], v[70:73]
	v_mfma_f32_16x16x32_bf16 v[66:69], v[146:149], v[218:221], v[66:69]
	v_mfma_f32_16x16x32_bf16 v[66:69], v[150:153], v[222:225], v[66:69]
	v_mfma_f32_16x16x32_bf16 v[22:25], v[154:157], v[162:165], v[22:25]
	v_mfma_f32_16x16x32_bf16 v[22:25], v[158:161], v[166:169], v[22:25]
	v_mfma_f32_16x16x32_bf16 v[14:17], v[154:157], v[188:191], v[14:17]
	v_mfma_f32_16x16x32_bf16 v[14:17], v[158:161], v[192:195], v[14:17]
	v_mfma_f32_16x16x32_bf16 v[6:9], v[154:157], v[196:199], v[6:9]
	v_mfma_f32_16x16x32_bf16 v[6:9], v[158:161], v[214:217], v[6:9]
	v_mfma_f32_16x16x32_bf16 v[2:5], v[154:157], v[218:221], v[2:5]
	v_mfma_f32_16x16x32_bf16 v[2:5], v[158:161], v[222:225], v[2:5]
	s_setprio 0
	s_barrier
	ds_read_b128 v[130:133], v226
	ds_read_b128 v[134:137], v226 offset:1024
	ds_read_b128 v[138:141], v226 offset:2048
	ds_read_b128 v[142:145], v226 offset:3072
	ds_read_b128 v[146:149], v227
	ds_read_b128 v[150:153], v227 offset:1024
	ds_read_b128 v[154:157], v227 offset:2048
	ds_read_b128 v[158:161], v227 offset:3072
	ds_read_b128 v[162:165], v212 offset:32768
	ds_read_b128 v[166:169], v212 offset:33792
	ds_read_b128 v[188:191], v212 offset:34816
	ds_read_b128 v[192:195], v212 offset:35840
	ds_read_b128 v[196:199], v212 offset:36864
	ds_read_b128 v[214:217], v212 offset:37888
	s_add_i32 m0, s39, 0x4000
	ds_read_b128 v[218:221], v212 offset:38912
	global_load_lds_dwordx4 v170, s[100:101]
	s_add_i32 m0, s39, 0x6000
	ds_read_b128 v[222:225], v212 offset:39936
	global_load_lds_dwordx4 v174, s[100:101]
	s_waitcnt vmcnt(8) lgkmcnt(0)
	s_barrier
	s_setprio 1
	v_mfma_f32_16x16x32_bf16 v[126:129], v[130:133], v[162:165], v[126:129]
	v_mfma_f32_16x16x32_bf16 v[126:129], v[134:137], v[166:169], v[126:129]
	v_mfma_f32_16x16x32_bf16 v[122:125], v[130:133], v[188:191], v[122:125]
	v_mfma_f32_16x16x32_bf16 v[122:125], v[134:137], v[192:195], v[122:125]
	v_mfma_f32_16x16x32_bf16 v[110:113], v[130:133], v[196:199], v[110:113]
	v_mfma_f32_16x16x32_bf16 v[110:113], v[134:137], v[214:217], v[110:113]
	v_mfma_f32_16x16x32_bf16 v[106:109], v[130:133], v[218:221], v[106:109]
	v_mfma_f32_16x16x32_bf16 v[106:109], v[134:137], v[222:225], v[106:109]
	v_mfma_f32_16x16x32_bf16 v[62:65], v[138:141], v[162:165], v[62:65]
	v_mfma_f32_16x16x32_bf16 v[62:65], v[142:145], v[166:169], v[62:65]
	v_mfma_f32_16x16x32_bf16 v[58:61], v[138:141], v[188:191], v[58:61]
	v_mfma_f32_16x16x32_bf16 v[58:61], v[142:145], v[192:195], v[58:61]
	v_mfma_f32_16x16x32_bf16 v[50:53], v[138:141], v[196:199], v[50:53]
	v_mfma_f32_16x16x32_bf16 v[50:53], v[142:145], v[214:217], v[50:53]
	v_mfma_f32_16x16x32_bf16 v[42:45], v[138:141], v[218:221], v[42:45]
	v_mfma_f32_16x16x32_bf16 v[42:45], v[142:145], v[222:225], v[42:45]
	v_mfma_f32_16x16x32_bf16 v[118:121], v[146:149], v[162:165], v[118:121]
	v_mfma_f32_16x16x32_bf16 v[118:121], v[150:153], v[166:169], v[118:121]
	v_mfma_f32_16x16x32_bf16 v[114:117], v[146:149], v[188:191], v[114:117]
	v_mfma_f32_16x16x32_bf16 v[114:117], v[150:153], v[192:195], v[114:117]
	v_mfma_f32_16x16x32_bf16 v[102:105], v[146:149], v[196:199], v[102:105]
	v_mfma_f32_16x16x32_bf16 v[102:105], v[150:153], v[214:217], v[102:105]
	v_mfma_f32_16x16x32_bf16 v[98:101], v[146:149], v[218:221], v[98:101]
	v_mfma_f32_16x16x32_bf16 v[98:101], v[150:153], v[222:225], v[98:101]
	v_mfma_f32_16x16x32_bf16 v[54:57], v[154:157], v[162:165], v[54:57]
	v_mfma_f32_16x16x32_bf16 v[54:57], v[158:161], v[166:169], v[54:57]
	v_mfma_f32_16x16x32_bf16 v[46:49], v[154:157], v[188:191], v[46:49]
	v_mfma_f32_16x16x32_bf16 v[46:49], v[158:161], v[192:195], v[46:49]
	v_mfma_f32_16x16x32_bf16 v[38:41], v[154:157], v[196:199], v[38:41]
	v_mfma_f32_16x16x32_bf16 v[38:41], v[158:161], v[214:217], v[38:41]
	v_mfma_f32_16x16x32_bf16 v[34:37], v[154:157], v[218:221], v[34:37]
	v_mfma_f32_16x16x32_bf16 v[34:37], v[158:161], v[222:225], v[34:37]
	s_setprio 0
	s_barrier
	ds_read_b128 v[162:165], v212 offset:49152
	ds_read_b128 v[166:169], v212 offset:50176
	s_add_i32 m0, s39, 0x17f80
	ds_read_b128 v[188:191], v212 offset:51200
	global_load_lds_dwordx4 v172, s[92:93] offset:128
	s_add_i32 m0, s39, 0x19f80
	ds_read_b128 v[192:195], v212 offset:52224
	global_load_lds_dwordx4 v176, s[92:93] offset:128
	s_add_i32 m0, s39, 0x1bf80
	ds_read_b128 v[196:199], v212 offset:53248
	global_load_lds_dwordx4 v172, s[98:99] offset:128
	s_add_i32 m0, s39, 0x1df80
	ds_read_b128 v[214:217], v212 offset:54272
	global_load_lds_dwordx4 v176, s[98:99] offset:128
	s_add_i32 m0, s39, 0x7f80
	ds_read_b128 v[218:221], v212 offset:55296
	global_load_lds_dwordx4 v170, s[94:95] offset:128
	s_add_i32 m0, s39, 0x9f80
	ds_read_b128 v[222:225], v212 offset:56320
	global_load_lds_dwordx4 v174, s[94:95] offset:128
	s_waitcnt vmcnt(8) lgkmcnt(0)
	s_barrier
	s_setprio 1
	v_mfma_f32_16x16x32_bf16 v[94:97], v[130:133], v[162:165], v[94:97]
	v_mfma_f32_16x16x32_bf16 v[94:97], v[134:137], v[166:169], v[94:97]
	v_mfma_f32_16x16x32_bf16 v[90:93], v[130:133], v[188:191], v[90:93]
	v_mfma_f32_16x16x32_bf16 v[90:93], v[134:137], v[192:195], v[90:93]
	v_mfma_f32_16x16x32_bf16 v[82:85], v[130:133], v[196:199], v[82:85]
	v_mfma_f32_16x16x32_bf16 v[82:85], v[134:137], v[214:217], v[82:85]
	v_mfma_f32_16x16x32_bf16 v[74:77], v[130:133], v[218:221], v[74:77]
	v_mfma_f32_16x16x32_bf16 v[74:77], v[134:137], v[222:225], v[74:77]
	v_mfma_f32_16x16x32_bf16 v[30:33], v[138:141], v[162:165], v[30:33]
	v_mfma_f32_16x16x32_bf16 v[30:33], v[142:145], v[166:169], v[30:33]
	v_mfma_f32_16x16x32_bf16 v[26:29], v[138:141], v[188:191], v[26:29]
	v_mfma_f32_16x16x32_bf16 v[26:29], v[142:145], v[192:195], v[26:29]
	v_mfma_f32_16x16x32_bf16 v[18:21], v[138:141], v[196:199], v[18:21]
	v_mfma_f32_16x16x32_bf16 v[18:21], v[142:145], v[214:217], v[18:21]
	v_mfma_f32_16x16x32_bf16 v[10:13], v[138:141], v[218:221], v[10:13]
	v_mfma_f32_16x16x32_bf16 v[10:13], v[142:145], v[222:225], v[10:13]
	v_mfma_f32_16x16x32_bf16 v[86:89], v[146:149], v[162:165], v[86:89]
	v_mfma_f32_16x16x32_bf16 v[86:89], v[150:153], v[166:169], v[86:89]
	v_mfma_f32_16x16x32_bf16 v[78:81], v[146:149], v[188:191], v[78:81]
	v_mfma_f32_16x16x32_bf16 v[78:81], v[150:153], v[192:195], v[78:81]
	v_mfma_f32_16x16x32_bf16 v[70:73], v[146:149], v[196:199], v[70:73]
	v_mfma_f32_16x16x32_bf16 v[70:73], v[150:153], v[214:217], v[70:73]
	v_mfma_f32_16x16x32_bf16 v[66:69], v[146:149], v[218:221], v[66:69]
	v_mfma_f32_16x16x32_bf16 v[66:69], v[150:153], v[222:225], v[66:69]
	v_mfma_f32_16x16x32_bf16 v[22:25], v[154:157], v[162:165], v[22:25]
	v_mfma_f32_16x16x32_bf16 v[22:25], v[158:161], v[166:169], v[22:25]
	v_mfma_f32_16x16x32_bf16 v[14:17], v[154:157], v[188:191], v[14:17]
	s_add_i32 s66, s66, 2
	v_mfma_f32_16x16x32_bf16 v[14:17], v[158:161], v[192:195], v[14:17]
	s_add_u32 vcc_lo, vcc_lo, 0x100
	v_mfma_f32_16x16x32_bf16 v[6:9], v[154:157], v[196:199], v[6:9]
	s_addc_u32 vcc_hi, vcc_hi, 0
	v_mfma_f32_16x16x32_bf16 v[6:9], v[158:161], v[214:217], v[6:9]
	s_mov_b64 s[88:89], s[90:91]
	v_mfma_f32_16x16x32_bf16 v[2:5], v[154:157], v[218:221], v[2:5]
	s_cmp_gt_u32 s66, 61
	v_mfma_f32_16x16x32_bf16 v[2:5], v[158:161], v[222:225], v[2:5]
	s_setprio 0
	s_barrier
	s_cbranch_scc0 .LBB0_651
	s_and_b64 vcc, exec, s[36:37]
	s_cbranch_vccz .LBB0_654
	s_barrier

.LBB0_834:
	ds_read_b128 v[146:149], v152
	ds_read_b128 v[156:159], v152 offset:1024
	ds_read_b128 v[160:163], v152 offset:2048
	ds_read_b128 v[164:167], v152 offset:3072
	ds_read_b128 v[168:171], v153
	ds_read_b128 v[172:175], v153 offset:1024
	ds_read_b128 v[176:179], v153 offset:2048
	ds_read_b128 v[180:183], v153 offset:3072
	ds_read_b128 v[184:187], v154
	ds_read_b128 v[188:191], v154 offset:1024
	ds_read_b128 v[192:195], v154 offset:2048
	ds_read_b128 v[196:199], v154 offset:3072
	ds_read_b128 v[206:209], v154 offset:4096
	ds_read_b128 v[210:213], v154 offset:5120
	s_add_i32 m0, s1, 0xc000
	ds_read_b128 v[214:217], v154 offset:6144
	global_load_lds_dwordx4 v138, s[42:43]
	s_add_i32 m0, s1, 0xe000
	ds_read_b128 v[218:221], v154 offset:7168
	global_load_lds_dwordx4 v140, s[42:43]
	s_waitcnt vmcnt(8) lgkmcnt(0)
	s_barrier
	s_setprio 1
	v_mfma_f32_16x16x32_bf16 v[126:129], v[146:149], v[184:187], v[126:129]
	v_mfma_f32_16x16x32_bf16 v[126:129], v[156:159], v[188:191], v[126:129]
	v_mfma_f32_16x16x32_bf16 v[110:113], v[146:149], v[192:195], v[110:113]
	s_add_u32 s34, s42, 0x1fc000
	v_mfma_f32_16x16x32_bf16 v[110:113], v[156:159], v[196:199], v[110:113]
	s_addc_u32 s44, s43, 0
	v_mfma_f32_16x16x32_bf16 v[94:97], v[146:149], v[206:209], v[94:97]
	s_cmpk_eq_i32 s61, 0xa8
	v_mfma_f32_16x16x32_bf16 v[94:97], v[156:159], v[210:213], v[94:97]
	s_cselect_b32 s48, s41, s34
	v_mfma_f32_16x16x32_bf16 v[78:81], v[146:149], v[214:217], v[78:81]
	s_cselect_b32 s49, s23, s44
	v_mfma_f32_16x16x32_bf16 v[78:81], v[156:159], v[218:221], v[78:81]
	s_cselect_b32 s47, s21, s60
	v_mfma_f32_16x16x32_bf16 v[122:125], v[160:163], v[184:187], v[122:125]
	s_cselect_b32 s46, s58, s59
	v_mfma_f32_16x16x32_bf16 v[122:125], v[164:167], v[188:191], v[122:125]
	s_add_u32 s44, s48, 0x200000
	v_mfma_f32_16x16x32_bf16 v[106:109], v[160:163], v[192:195], v[106:109]
	s_addc_u32 s45, s49, 0
	v_mfma_f32_16x16x32_bf16 v[106:109], v[164:167], v[196:199], v[106:109]
	s_add_u32 s62, s46, 0x4000
	v_mfma_f32_16x16x32_bf16 v[90:93], v[160:163], v[206:209], v[90:93]
	s_addc_u32 s63, s47, 0
	v_mfma_f32_16x16x32_bf16 v[90:93], v[164:167], v[210:213], v[90:93]
	s_add_u32 s100, s48, 0x4000
	v_mfma_f32_16x16x32_bf16 v[74:77], v[160:163], v[214:217], v[74:77]
	s_addc_u32 s101, s49, 0
	v_mfma_f32_16x16x32_bf16 v[74:77], v[164:167], v[218:221], v[74:77]
	s_add_u32 s98, s46, 0x80000
	v_mfma_f32_16x16x32_bf16 v[118:121], v[168:171], v[184:187], v[118:121]
	s_addc_u32 s99, s47, 0
	v_mfma_f32_16x16x32_bf16 v[118:121], v[172:175], v[188:191], v[118:121]
	s_add_u32 s24, s46, 0x84000
	v_mfma_f32_16x16x32_bf16 v[102:105], v[168:171], v[192:195], v[102:105]
	s_addc_u32 s25, s47, 0
	v_mfma_f32_16x16x32_bf16 v[102:105], v[172:175], v[196:199], v[102:105]
	v_mfma_f32_16x16x32_bf16 v[86:89], v[168:171], v[206:209], v[86:89]
	v_mfma_f32_16x16x32_bf16 v[86:89], v[172:175], v[210:213], v[86:89]
	v_mfma_f32_16x16x32_bf16 v[70:73], v[168:171], v[214:217], v[70:73]
	v_mfma_f32_16x16x32_bf16 v[70:73], v[172:175], v[218:221], v[70:73]
	v_mfma_f32_16x16x32_bf16 v[114:117], v[176:179], v[184:187], v[114:117]
	v_mfma_f32_16x16x32_bf16 v[114:117], v[180:183], v[188:191], v[114:117]
	v_mfma_f32_16x16x32_bf16 v[98:101], v[176:179], v[192:195], v[98:101]
	v_mfma_f32_16x16x32_bf16 v[98:101], v[180:183], v[196:199], v[98:101]
	v_mfma_f32_16x16x32_bf16 v[82:85], v[176:179], v[206:209], v[82:85]
	v_mfma_f32_16x16x32_bf16 v[82:85], v[180:183], v[210:213], v[82:85]
	v_mfma_f32_16x16x32_bf16 v[66:69], v[176:179], v[214:217], v[66:69]
	v_mfma_f32_16x16x32_bf16 v[66:69], v[180:183], v[218:221], v[66:69]
	s_setprio 0
	s_barrier
	ds_read_b128 v[184:187], v154 offset:16384
	ds_read_b128 v[188:191], v154 offset:17408
	s_add_i32 m0, s1, 0x10000
	ds_read_b128 v[192:195], v154 offset:18432
	global_load_lds_dwordx4 v132, s[46:47]
	s_add_i32 m0, s1, 0x12000
	ds_read_b128 v[196:199], v154 offset:19456
	global_load_lds_dwordx4 v136, s[46:47]
	s_add_i32 m0, s1, 0x14000
	ds_read_b128 v[206:209], v154 offset:20480
	global_load_lds_dwordx4 v132, s[62:63]
	s_add_i32 m0, s1, 0x16000
	ds_read_b128 v[210:213], v154 offset:21504
	global_load_lds_dwordx4 v136, s[62:63]
	s_mov_b32 m0, s1
	ds_read_b128 v[214:217], v154 offset:22528
	global_load_lds_dwordx4 v130, s[48:49]
	s_add_i32 m0, s1, 0x2000
	ds_read_b128 v[218:221], v154 offset:23552
	global_load_lds_dwordx4 v134, s[48:49]
	s_waitcnt vmcnt(8) lgkmcnt(0)
	s_barrier
	s_setprio 1
	v_mfma_f32_16x16x32_bf16 v[62:65], v[146:149], v[184:187], v[62:65]
	v_mfma_f32_16x16x32_bf16 v[62:65], v[156:159], v[188:191], v[62:65]
	v_mfma_f32_16x16x32_bf16 v[46:49], v[146:149], v[192:195], v[46:49]
	v_mfma_f32_16x16x32_bf16 v[46:49], v[156:159], v[196:199], v[46:49]
	v_mfma_f32_16x16x32_bf16 v[30:33], v[146:149], v[206:209], v[30:33]
	v_mfma_f32_16x16x32_bf16 v[30:33], v[156:159], v[210:213], v[30:33]
	v_mfma_f32_16x16x32_bf16 v[14:17], v[146:149], v[214:217], v[14:17]
	v_mfma_f32_16x16x32_bf16 v[14:17], v[156:159], v[218:221], v[14:17]
	v_mfma_f32_16x16x32_bf16 v[58:61], v[160:163], v[184:187], v[58:61]
	v_mfma_f32_16x16x32_bf16 v[58:61], v[164:167], v[188:191], v[58:61]
	v_mfma_f32_16x16x32_bf16 v[42:45], v[160:163], v[192:195], v[42:45]
	v_mfma_f32_16x16x32_bf16 v[42:45], v[164:167], v[196:199], v[42:45]
	v_mfma_f32_16x16x32_bf16 v[26:29], v[160:163], v[206:209], v[26:29]
	v_mfma_f32_16x16x32_bf16 v[26:29], v[164:167], v[210:213], v[26:29]
	v_mfma_f32_16x16x32_bf16 v[10:13], v[160:163], v[214:217], v[10:13]
	v_mfma_f32_16x16x32_bf16 v[10:13], v[164:167], v[218:221], v[10:13]
	v_mfma_f32_16x16x32_bf16 v[54:57], v[168:171], v[184:187], v[54:57]
	v_mfma_f32_16x16x32_bf16 v[54:57], v[172:175], v[188:191], v[54:57]
	v_mfma_f32_16x16x32_bf16 v[38:41], v[168:171], v[192:195], v[38:41]
	v_mfma_f32_16x16x32_bf16 v[38:41], v[172:175], v[196:199], v[38:41]
	v_mfma_f32_16x16x32_bf16 v[22:25], v[168:171], v[206:209], v[22:25]
	v_mfma_f32_16x16x32_bf16 v[22:25], v[172:175], v[210:213], v[22:25]
	v_mfma_f32_16x16x32_bf16 v[6:9], v[168:171], v[214:217], v[6:9]
	v_mfma_f32_16x16x32_bf16 v[6:9], v[172:175], v[218:221], v[6:9]
	v_mfma_f32_16x16x32_bf16 v[50:53], v[176:179], v[184:187], v[50:53]
	v_mfma_f32_16x16x32_bf16 v[50:53], v[180:183], v[188:191], v[50:53]
	v_mfma_f32_16x16x32_bf16 v[34:37], v[176:179], v[192:195], v[34:37]
	v_mfma_f32_16x16x32_bf16 v[34:37], v[180:183], v[196:199], v[34:37]
	v_mfma_f32_16x16x32_bf16 v[18:21], v[176:179], v[206:209], v[18:21]
	v_mfma_f32_16x16x32_bf16 v[18:21], v[180:183], v[210:213], v[18:21]
	v_mfma_f32_16x16x32_bf16 v[2:5], v[176:179], v[214:217], v[2:5]
	v_mfma_f32_16x16x32_bf16 v[2:5], v[180:183], v[218:221], v[2:5]
	s_setprio 0
	s_barrier
	ds_read_b128 v[146:149], v226
	ds_read_b128 v[156:159], v226 offset:1024
	ds_read_b128 v[160:163], v226 offset:2048
	ds_read_b128 v[164:167], v226 offset:3072
	ds_read_b128 v[168:171], v227
	ds_read_b128 v[172:175], v227 offset:1024
	ds_read_b128 v[176:179], v227 offset:2048
	ds_read_b128 v[180:183], v227 offset:3072
	ds_read_b128 v[184:187], v154 offset:32768
	ds_read_b128 v[188:191], v154 offset:33792
	ds_read_b128 v[192:195], v154 offset:34816
	ds_read_b128 v[196:199], v154 offset:35840
	ds_read_b128 v[206:209], v154 offset:36864
	ds_read_b128 v[210:213], v154 offset:37888
	s_add_i32 m0, s1, 0x4000
	ds_read_b128 v[214:217], v154 offset:38912
	global_load_lds_dwordx4 v130, s[100:101]
	s_add_i32 m0, s1, 0x6000
	ds_read_b128 v[218:221], v154 offset:39936
	global_load_lds_dwordx4 v134, s[100:101]
	s_waitcnt vmcnt(8) lgkmcnt(0)
	s_barrier
	s_setprio 1
	v_mfma_f32_16x16x32_bf16 v[126:129], v[146:149], v[184:187], v[126:129]
	v_mfma_f32_16x16x32_bf16 v[126:129], v[156:159], v[188:191], v[126:129]
	v_mfma_f32_16x16x32_bf16 v[110:113], v[146:149], v[192:195], v[110:113]
	v_mfma_f32_16x16x32_bf16 v[110:113], v[156:159], v[196:199], v[110:113]
	v_mfma_f32_16x16x32_bf16 v[94:97], v[146:149], v[206:209], v[94:97]
	v_mfma_f32_16x16x32_bf16 v[94:97], v[156:159], v[210:213], v[94:97]
	v_mfma_f32_16x16x32_bf16 v[78:81], v[146:149], v[214:217], v[78:81]
	v_mfma_f32_16x16x32_bf16 v[78:81], v[156:159], v[218:221], v[78:81]
	v_mfma_f32_16x16x32_bf16 v[122:125], v[160:163], v[184:187], v[122:125]
	v_mfma_f32_16x16x32_bf16 v[122:125], v[164:167], v[188:191], v[122:125]
	v_mfma_f32_16x16x32_bf16 v[106:109], v[160:163], v[192:195], v[106:109]
	v_mfma_f32_16x16x32_bf16 v[106:109], v[164:167], v[196:199], v[106:109]
	v_mfma_f32_16x16x32_bf16 v[90:93], v[160:163], v[206:209], v[90:93]
	v_mfma_f32_16x16x32_bf16 v[90:93], v[164:167], v[210:213], v[90:93]
	v_mfma_f32_16x16x32_bf16 v[74:77], v[160:163], v[214:217], v[74:77]
	v_mfma_f32_16x16x32_bf16 v[74:77], v[164:167], v[218:221], v[74:77]
	v_mfma_f32_16x16x32_bf16 v[118:121], v[168:171], v[184:187], v[118:121]
	v_mfma_f32_16x16x32_bf16 v[118:121], v[172:175], v[188:191], v[118:121]
	v_mfma_f32_16x16x32_bf16 v[102:105], v[168:171], v[192:195], v[102:105]
	v_mfma_f32_16x16x32_bf16 v[102:105], v[172:175], v[196:199], v[102:105]
	v_mfma_f32_16x16x32_bf16 v[86:89], v[168:171], v[206:209], v[86:89]
	v_mfma_f32_16x16x32_bf16 v[86:89], v[172:175], v[210:213], v[86:89]
	v_mfma_f32_16x16x32_bf16 v[70:73], v[168:171], v[214:217], v[70:73]
	v_mfma_f32_16x16x32_bf16 v[70:73], v[172:175], v[218:221], v[70:73]
	v_mfma_f32_16x16x32_bf16 v[114:117], v[176:179], v[184:187], v[114:117]
	v_mfma_f32_16x16x32_bf16 v[114:117], v[180:183], v[188:191], v[114:117]
	v_mfma_f32_16x16x32_bf16 v[98:101], v[176:179], v[192:195], v[98:101]
	v_mfma_f32_16x16x32_bf16 v[98:101], v[180:183], v[196:199], v[98:101]
	v_mfma_f32_16x16x32_bf16 v[82:85], v[176:179], v[206:209], v[82:85]
	v_mfma_f32_16x16x32_bf16 v[82:85], v[180:183], v[210:213], v[82:85]
	v_mfma_f32_16x16x32_bf16 v[66:69], v[176:179], v[214:217], v[66:69]
	v_mfma_f32_16x16x32_bf16 v[66:69], v[180:183], v[218:221], v[66:69]
	s_setprio 0
	s_barrier
	ds_read_b128 v[184:187], v154 offset:49152
	ds_read_b128 v[188:191], v154 offset:50176
	s_add_i32 m0, s1, 0x18000
	ds_read_b128 v[192:195], v154 offset:51200
	global_load_lds_dwordx4 v132, s[98:99]
	s_add_i32 m0, s1, 0x1a000
	ds_read_b128 v[196:199], v154 offset:52224
	global_load_lds_dwordx4 v136, s[98:99]
	s_add_i32 m0, s1, 0x1c000
	ds_read_b128 v[206:209], v154 offset:53248
	global_load_lds_dwordx4 v132, s[24:25]
	s_add_i32 m0, s1, 0x1e000
	ds_read_b128 v[210:213], v154 offset:54272
	global_load_lds_dwordx4 v136, s[24:25]
	s_add_i32 m0, s1, 0x8000
	ds_read_b128 v[214:217], v154 offset:55296
	global_load_lds_dwordx4 v130, s[44:45]
	s_add_i32 m0, s1, 0xa000
	ds_read_b128 v[218:221], v154 offset:56320
	global_load_lds_dwordx4 v134, s[44:45]
	s_waitcnt vmcnt(8) lgkmcnt(0)
	s_barrier
	s_setprio 1
	v_mfma_f32_16x16x32_bf16 v[62:65], v[146:149], v[184:187], v[62:65]
	v_mfma_f32_16x16x32_bf16 v[62:65], v[156:159], v[188:191], v[62:65]
	v_mfma_f32_16x16x32_bf16 v[46:49], v[146:149], v[192:195], v[46:49]
	v_mfma_f32_16x16x32_bf16 v[46:49], v[156:159], v[196:199], v[46:49]
	v_mfma_f32_16x16x32_bf16 v[30:33], v[146:149], v[206:209], v[30:33]
	v_mfma_f32_16x16x32_bf16 v[30:33], v[156:159], v[210:213], v[30:33]
	v_mfma_f32_16x16x32_bf16 v[14:17], v[146:149], v[214:217], v[14:17]
	v_mfma_f32_16x16x32_bf16 v[14:17], v[156:159], v[218:221], v[14:17]
	v_mfma_f32_16x16x32_bf16 v[58:61], v[160:163], v[184:187], v[58:61]
	v_mfma_f32_16x16x32_bf16 v[58:61], v[164:167], v[188:191], v[58:61]
	v_mfma_f32_16x16x32_bf16 v[42:45], v[160:163], v[192:195], v[42:45]
	v_mfma_f32_16x16x32_bf16 v[42:45], v[164:167], v[196:199], v[42:45]
	v_mfma_f32_16x16x32_bf16 v[26:29], v[160:163], v[206:209], v[26:29]
	v_mfma_f32_16x16x32_bf16 v[26:29], v[164:167], v[210:213], v[26:29]
	v_mfma_f32_16x16x32_bf16 v[10:13], v[160:163], v[214:217], v[10:13]
	v_mfma_f32_16x16x32_bf16 v[10:13], v[164:167], v[218:221], v[10:13]
	v_mfma_f32_16x16x32_bf16 v[54:57], v[168:171], v[184:187], v[54:57]
	v_mfma_f32_16x16x32_bf16 v[54:57], v[172:175], v[188:191], v[54:57]
	v_mfma_f32_16x16x32_bf16 v[38:41], v[168:171], v[192:195], v[38:41]
	v_mfma_f32_16x16x32_bf16 v[38:41], v[172:175], v[196:199], v[38:41]
	v_mfma_f32_16x16x32_bf16 v[22:25], v[168:171], v[206:209], v[22:25]
	v_mfma_f32_16x16x32_bf16 v[22:25], v[172:175], v[210:213], v[22:25]
	v_mfma_f32_16x16x32_bf16 v[6:9], v[168:171], v[214:217], v[6:9]
	v_mfma_f32_16x16x32_bf16 v[6:9], v[172:175], v[218:221], v[6:9]
	v_mfma_f32_16x16x32_bf16 v[50:53], v[176:179], v[184:187], v[50:53]
	v_mfma_f32_16x16x32_bf16 v[50:53], v[180:183], v[188:191], v[50:53]
	s_add_i32 s61, s61, 2
	v_mfma_f32_16x16x32_bf16 v[34:37], v[176:179], v[192:195], v[34:37]
	s_add_u32 s59, s59, 0x100000
	v_mfma_f32_16x16x32_bf16 v[34:37], v[180:183], v[196:199], v[34:37]
	s_addc_u32 s60, s60, 0
	v_mfma_f32_16x16x32_bf16 v[18:21], v[176:179], v[206:209], v[18:21]
	s_add_u32 s42, s42, 0x400000
	v_mfma_f32_16x16x32_bf16 v[18:21], v[180:183], v[210:213], v[18:21]
	s_addc_u32 s43, s43, 0
	v_mfma_f32_16x16x32_bf16 v[2:5], v[176:179], v[214:217], v[2:5]
	s_cmpk_gt_u32 s61, 0xa9
	v_mfma_f32_16x16x32_bf16 v[2:5], v[180:183], v[218:221], v[2:5]
	s_setprio 0
	s_barrier
	s_cbranch_scc0 .LBB0_834
	s_and_b64 vcc, exec, s[18:19]
	s_cbranch_vccz .LBB0_837
	s_barrier
